# rotK with the bias-table reads after the 4th PV MFMA in BOTH the FoX and band loops
# baseline (speedup 1.0000x reference)
; #define LAS __attribute__((address_space(3)))
; template <int MODE>
; __device__ __forceinline__ void step64(St& S, const bf16x8 (&qf)[4], int t, int qpos0, bool diag, bool first, float cq, float cfar, const LAS float* tab,
;                                        const LAS unsigned char* buf, unsigned vaddr, int r32, int hi) {
;     ...
;     if (MODE == 1) {
;         const float nm = cq - S.m;
; #pragma unroll
;         for (int g = 0; g < 4; ++g) { const f32x4 c0 = *(const LAS f32x4*)(tab + t * 64 + 8 * g + 4 * hi), c1 = *(const LAS f32x4*)(tab + t * 64 + 32 + 8 * g + 4 * hi);
; #pragma unroll
;             for (int e = 0; e < 4; ++e) { sa[4 * g + e] = nm - c0[e]; sb[4 * g + e] = nm - c1[e]; } }
;     ...
;     for (int r = 0; r < 16; ++r) { sa[r] = __builtin_amdgcn_exp2f(sa[r]); sb[r] = __builtin_amdgcn_exp2f(sb[r]); }
;     asm volatile("s_waitcnt lgkmcnt(0)" ::: "memory");
;     __builtin_amdgcn_sched_barrier(0);
;     u32x4 pa0, pa1, pb0, pb1;
;     pa0.x = pk2(sa[0], sa[1]); pa0.y = pk2(sa[2], sa[3]); pa0.z = pk2(sa[4], sa[5]); pa0.w = pk2(sa[6], sa[7]);
;     pa1.x = pk2(sa[8], sa[9]); pa1.y = pk2(sa[10], sa[11]); pa1.z = pk2(sa[12], sa[13]); pa1.w = pk2(sa[14], sa[15]);
;     pb0.x = pk2(sb[0], sb[1]); pb0.y = pk2(sb[2], sb[3]); pb0.z = pk2(sb[4], sb[5]); pb0.w = pk2(sb[6], sb[7]);
;     pb1.x = pk2(sb[8], sb[9]); pb1.y = pk2(sb[10], sb[11]); pb1.z = pk2(sb[12], sb[13]); pb1.w = pk2(sb[14], sb[15]);
;     ...
;     S.o0 = __builtin_amdgcn_mfma_f32_32x32x16_bf16(ATT_VF(0), ATT_PF(pa0), S.o0, 0, 0, 0);
;     S.o1 = __builtin_amdgcn_mfma_f32_32x32x16_bf16(ATT_VF(2), ATT_PF(pa0), S.o1, 0, 0, 0);
;     S.o0 = __builtin_amdgcn_mfma_f32_32x32x16_bf16(ATT_VF(1), ATT_PF(pa1), S.o0, 0, 0, 0);
;     S.o1 = __builtin_amdgcn_mfma_f32_32x32x16_bf16(ATT_VF(3), ATT_PF(pa1), S.o1, 0, 0, 0);
;     S.o0 = __builtin_amdgcn_mfma_f32_32x32x16_bf16(ATT_VF(4), ATT_PF(pb0), S.o0, 0, 0, 0);
;     S.o1 = __builtin_amdgcn_mfma_f32_32x32x16_bf16(ATT_VF(6), ATT_PF(pb0), S.o1, 0, 0, 0);
;     S.o0 = __builtin_amdgcn_mfma_f32_32x32x16_bf16(ATT_VF(5), ATT_PF(pb1), S.o0, 0, 0, 0);
;     S.o1 = __builtin_amdgcn_mfma_f32_32x32x16_bf16(ATT_VF(7), ATT_PF(pb1), S.o1, 0, 0, 0);
;     ...
;     float l0 = 0.f, l1 = 0.f, l2 = 0.f, l3 = 0.f;
; #pragma unroll
;     for (int r = 0; r < 16; r += 2) { l0 += sa[r]; l1 += sa[r + 1]; l2 += sb[r]; l3 += sb[r + 1]; }
;     S.l += (l0 + l1) + (l2 + l3);
.Lk1_nodma:
	s_cmp_lt_i32 s22, s28
	s_cbranch_scc0 .Lk1_noY
	v_exp_f32_e32 v48, v48
	v_exp_f32_e32 v49, v49
	v_exp_f32_e32 v50, v50
	v_exp_f32_e32 v51, v51
	v_exp_f32_e32 v52, v52
	v_exp_f32_e32 v53, v53
	v_exp_f32_e32 v54, v54
	v_exp_f32_e32 v55, v55
	v_cvt_pk_bf16_f32 v152, v48, v49
	v_cvt_pk_bf16_f32 v153, v50, v51
	v_cvt_pk_bf16_f32 v154, v52, v53
	v_cvt_pk_bf16_f32 v155, v54, v55
	v_exp_f32_e32 v56, v56
	v_exp_f32_e32 v57, v57
	v_mfma_f32_32x32x16_bf16 v[32:47], v[112:115], v[152:155], v[32:47]
	v_exp_f32_e32 v58, v58
	v_exp_f32_e32 v59, v59
	v_exp_f32_e32 v60, v60
	v_exp_f32_e32 v61, v61
	v_exp_f32_e32 v62, v62
	v_exp_f32_e32 v63, v63
	v_mfma_f32_32x32x16_bf16 v[16:31], v[108:111], v[152:155], v[16:31]
	v_cvt_pk_bf16_f32 v156, v56, v57
	v_cvt_pk_bf16_f32 v157, v58, v59
	v_cvt_pk_bf16_f32 v158, v60, v61
	v_cvt_pk_bf16_f32 v159, v62, v63
	v_add_f32_e32 v0, v48, v50
	v_add_f32_e32 v0, v0, v52
	v_add_f32_e32 v14, v49, v51
	v_add_f32_e32 v14, v14, v53
	v_mfma_f32_32x32x16_bf16 v[32:47], v[104:107], v[156:159], v[32:47]
	v_exp_f32_e32 v64, v64
	v_exp_f32_e32 v65, v65
	v_exp_f32_e32 v66, v66
	v_exp_f32_e32 v67, v67
	v_exp_f32_e32 v68, v68
	v_exp_f32_e32 v69, v69
	v_exp_f32_e32 v70, v70
	v_exp_f32_e32 v71, v71
	v_mfma_f32_32x32x16_bf16 v[16:31], v[100:103], v[156:159], v[16:31]
	s_waitcnt lgkmcnt(0)
	ds_read_b128 v[164:167], v148
	ds_read_b128 v[168:171], v148 offset:32
	ds_read_b128 v[172:175], v148 offset:64
	ds_read_b128 v[180:183], v148 offset:96
	ds_read_b128 v[218:221], v148 offset:128
	ds_read_b128 v[222:225], v148 offset:160
	ds_read_b128 v[226:229], v148 offset:192
	ds_read_b128 v[230:233], v148 offset:224
	v_cvt_pk_bf16_f32 v160, v64, v65
	v_cvt_pk_bf16_f32 v161, v66, v67
	v_cvt_pk_bf16_f32 v162, v68, v69
	v_cvt_pk_bf16_f32 v163, v70, v71
	v_add_f32_e32 v0, v0, v54
	v_add_f32_e32 v0, v0, v56
	v_add_f32_e32 v14, v14, v55
	v_add_f32_e32 v14, v14, v57
	v_mfma_f32_32x32x16_bf16 v[32:47], v[96:99], v[160:163], v[32:47]
	v_exp_f32_e32 v72, v72
	v_exp_f32_e32 v73, v73
	v_exp_f32_e32 v74, v74
	v_exp_f32_e32 v75, v75
	v_exp_f32_e32 v76, v76
	v_exp_f32_e32 v77, v77
	v_exp_f32_e32 v78, v78
	v_exp_f32_e32 v79, v79
	v_mfma_f32_32x32x16_bf16 v[16:31], v[10:13], v[160:163], v[16:31]
	v_cvt_pk_bf16_f32 v234, v72, v73
	v_cvt_pk_bf16_f32 v235, v74, v75
	v_cvt_pk_bf16_f32 v236, v76, v77
	v_cvt_pk_bf16_f32 v237, v78, v79
	v_add_f32_e32 v0, v0, v58
	v_add_f32_e32 v0, v0, v60
	v_add_f32_e32 v0, v0, v62
	v_add_f32_e32 v14, v14, v59
	v_add_f32_e32 v14, v14, v61
	v_add_f32_e32 v14, v14, v63
	v_mfma_f32_32x32x16_bf16 v[32:47], v[6:9], v[234:237], v[32:47]
	v_add_f32_e32 v15, v64, v66
	v_add_f32_e32 v15, v15, v68
	v_add_f32_e32 v15, v15, v70
	v_add_f32_e32 v15, v15, v72
	v_add_f32_e32 v151, v65, v67
	v_add_f32_e32 v151, v151, v69
	v_add_f32_e32 v151, v151, v71
	v_add_f32_e32 v151, v151, v73
	v_mfma_f32_32x32x16_bf16 v[16:31], v[2:5], v[234:237], v[16:31]
	v_add_f32_e32 v15, v15, v74
	v_add_f32_e32 v15, v15, v76
	v_add_f32_e32 v15, v15, v78
	v_add_f32_e32 v151, v151, v75
	v_add_f32_e32 v151, v151, v77
	v_add_f32_e32 v151, v151, v79
	v_add_f32_e32 v0, v0, v14
	v_add_f32_e32 v15, v15, v151
	v_add_f32_e32 v0, v0, v15
	v_add_f32_e32 v149, v149, v0
	v_sub_f32_e32 v151, v142, v150
	s_waitcnt lgkmcnt(0)
	v_sub_f32_e32 v48, v151, v164
	v_sub_f32_e32 v49, v151, v165
	v_sub_f32_e32 v50, v151, v166
	v_sub_f32_e32 v51, v151, v167
	v_sub_f32_e32 v52, v151, v168
	v_sub_f32_e32 v53, v151, v169
	v_sub_f32_e32 v54, v151, v170
	v_sub_f32_e32 v55, v151, v171
	v_sub_f32_e32 v56, v151, v172
	v_sub_f32_e32 v57, v151, v173
	v_sub_f32_e32 v58, v151, v174
	v_sub_f32_e32 v59, v151, v175
	v_sub_f32_e32 v60, v151, v180
	v_sub_f32_e32 v61, v151, v181
	v_sub_f32_e32 v62, v151, v182
	v_sub_f32_e32 v63, v151, v183
	v_sub_f32_e32 v64, v151, v218
	v_sub_f32_e32 v65, v151, v219
	v_sub_f32_e32 v66, v151, v220
	v_sub_f32_e32 v67, v151, v221
	v_sub_f32_e32 v68, v151, v222
	v_sub_f32_e32 v69, v151, v223
	v_sub_f32_e32 v70, v151, v224
	v_sub_f32_e32 v71, v151, v225
	v_sub_f32_e32 v72, v151, v226
	v_sub_f32_e32 v73, v151, v227
	v_sub_f32_e32 v74, v151, v228
	v_sub_f32_e32 v75, v151, v229
	v_sub_f32_e32 v76, v151, v230
	v_sub_f32_e32 v77, v151, v231
	v_sub_f32_e32 v78, v151, v232
	v_sub_f32_e32 v79, v151, v233
